# all 6 seams use the hand-written XCD barrier (seam 0 keeps its census, then the same arrive/post/poll protocol); on top of v061
# speedup vs baseline: 1.0016x; 1.0016x over previous
; __device__ __forceinline__ unsigned xb_ld(unsigned* p)              { return __hip_atomic_load(p, __ATOMIC_RELAXED, __HIP_MEMORY_SCOPE_AGENT); }
; __device__ __forceinline__ unsigned xb_add(unsigned* p, unsigned v) { return __hip_atomic_fetch_add(p, v, __ATOMIC_RELAXED, __HIP_MEMORY_SCOPE_AGENT); }
; #define XB_SPIN(cond, bar) do { unsigned _sp = 0; while (cond) { __builtin_amdgcn_s_sleep(1); \
;     if ((++_sp & 255u) == 0u) { if (xb_ld(&(bar)[XB_TMO])) break; if (_sp > XB_SPIN_CAP) { atomicAdd(&(bar)[XB_TMO], 1u); break; } } } } while (0)
; __device__ __forceinline__ void xcd_barrier(unsigned* bar, volatile LAS unsigned* st, bool is_t0) {
;     ...
;         if (nloc == 0u) { xcd_barrier_complete(bar, x, nloc, nx); st[0] = nloc; st[1] = nx; }
;         const unsigned old = xb_add(&bar[XB_XSUB(x)], 1u);
;         const unsigned gen = old / nloc;
;         if (old + 1u == (gen + 1u) * nloc) {
;             __builtin_amdgcn_fence(__ATOMIC_RELEASE, "agent");
;             asm volatile("s_waitcnt vmcnt(0)" ::: "memory");
;             const unsigned og = xb_add(&bar[XB_TOP], 1u);
;             const unsigned tg = og / nx;
;             if (og + 1u == (tg + 1u) * nx) xb_add(&bar[XB_TOPGEN], 1u);
;             else XB_SPIN(xb_ld(&bar[XB_TOPGEN]) == tg, bar);
;             __builtin_amdgcn_fence(__ATOMIC_ACQUIRE, "agent");
;             xb_add(&bar[XB_XGEN(x)], 1u);
;             asm volatile("s_waitcnt vmcnt(0)" ::: "memory");
;         } else {
;             XB_SPIN(xb_ld(&bar[XB_XGEN(x)]) == gen, bar);
;             __builtin_amdgcn_fence(__ATOMIC_ACQUIRE, "agent");
;             asm volatile("s_waitcnt vmcnt(0)" ::: "memory");
;         }
;     }
;     __syncthreads();
.Lsx0_180:
	s_waitcnt vmcnt(0) expcnt(0) lgkmcnt(0)
	v_mov_b32_e32 v250, 0x24080
	ds_read_b64 v[250:251], v250
	s_getreg_b32 s90, hwreg(HW_REG_XCC_ID, 0, 4)
	s_and_b32 s90, s90, 15
	s_lshl_b32 s91, s90, 8
	s_add_u32 s92, s34, s91
	s_addc_u32 s93, s35, 0
	s_add_u32 s92, s92, 0x1000
	s_addc_u32 s93, s93, 0
	s_add_u32 s94, s34, 0x3600
	s_addc_u32 s95, s35, 0
	s_lshl_b32 s91, s90, 7
	s_add_u32 s96, s94, s91
	s_addc_u32 s97, s95, 0
	v_mov_b32_e32 v253, 0
	v_mov_b32_e32 v252, 1
	s_waitcnt lgkmcnt(0)
	v_readfirstlane_b32 s98, v250
	v_readfirstlane_b32 s99, v251
	global_atomic_add v250, v253, v252, s[92:93] offset:1024 sc0
	s_mul_i32 s98, s98, 1
	s_mul_i32 s99, s99, 1
	s_waitcnt vmcnt(0)
	v_readfirstlane_b32 s91, v250
	s_add_i32 s91, s91, 1
	s_cmp_lg_u32 s91, s98
	s_cbranch_scc1 .Lfb0_poll
	buffer_wbl2 sc1
	s_waitcnt vmcnt(0)
	global_atomic_add v253, v252, s[94:95]
	global_atomic_add v253, v252, s[94:95] offset:128
	global_atomic_add v253, v252, s[94:95] offset:256
	global_atomic_add v253, v252, s[94:95] offset:384
	global_atomic_add v253, v252, s[94:95] offset:512
	global_atomic_add v253, v252, s[94:95] offset:640
	global_atomic_add v253, v252, s[94:95] offset:768
	global_atomic_add v253, v252, s[94:95] offset:896
	global_atomic_add v253, v252, s[94:95] offset:1024
	global_atomic_add v253, v252, s[94:95] offset:1152
	global_atomic_add v253, v252, s[94:95] offset:1280
	global_atomic_add v253, v252, s[94:95] offset:1408
	global_atomic_add v253, v252, s[94:95] offset:1536
	global_atomic_add v253, v252, s[94:95] offset:1664
	global_atomic_add v253, v252, s[94:95] offset:1792
	global_atomic_add v253, v252, s[94:95] offset:1920

;     __device__ bool next(int i, Unit& u) const {
;         const int ti = halves == 2 ? (i >> 1) : i; u.half = halves == 2 ? (i & 1) : 0;
;     ...
;         if (G == 256 && nM == 32 && (nN & 7) == 0) {
;             if (ti >= (nN >> 3)) return false;
;             const int x = c & 7, j = c >> 3; u.pm = 4 * x + (j & 3); u.pn = 8 * ti + (j >> 2); return true;
;         }
;     ...
;         const long L = (long)ti * G + c; if (L >= nwg) return false;
;         int wgid = (int)L; { const int q = nwg / NXCD, r = nwg % NXCD, xcd = wgid % NXCD, off = wgid / NXCD; wgid = (xcd < r ? xcd * (q + 1) : r * (q + 1) + (xcd - r) * q) + off; }
;         const int nig = wgm * nN, gid = wgid / nig, fm = gid * wgm, gsz = (nM - fm) < wgm ? (nM - fm) : wgm;
;         u.pm = fm + ((wgid % nig) % gsz); u.pn = (wgid % nig) / gsz; return true;
.Lfb0_done:
	buffer_inv sc1
	s_waitcnt vmcnt(0)
.Lsx0_217:
	s_or_b64 exec, exec, s[0:1]
	s_cmpk_lt_i32 s2, 0x800
	s_cselect_b64 s[0:1], -1, 0
	s_ashr_i32 s3, s2, 31
	s_lshr_b32 s4, s3, 29
	s_add_i32 s4, s2, s4
	s_ashr_i32 s64, s4, 3
	s_and_b32 s4, s4, -8
	s_sub_i32 s65, s2, s4
	s_cmp_lt_i32 s65, 0
	s_cselect_b64 s[40:41], -1, 0
	s_cmp_gt_i32 s65, -1
	s_cselect_b64 s[38:39], -1, 0
	s_add_i32 s4, 0, 0x24040
	v_mov_b32_e32 v0, s4
	s_add_i32 s4, 0, 0x24060
	s_barrier
	ds_read_b64 v[0:1], v0
	v_mov_b32_e32 v2, s4
	ds_read_b64 v[2:3], v2
	v_mbcnt_lo_u32_b32 v8, -1, 0
	v_mbcnt_hi_u32_b32 v8, -1, v8
	s_and_b64 vcc, exec, s[0:1]
	s_waitcnt lgkmcnt(1)
	v_readfirstlane_b32 s8, v0
	v_or_b32_e32 v0, s33, v8
	v_readfirstlane_b32 s9, v1
	s_waitcnt lgkmcnt(0)
	v_readfirstlane_b32 s7, v3
	v_readfirstlane_b32 s53, v2
	v_readfirstlane_b32 s16, v0
	s_cbranch_vccz .LBB0_88
	s_lshl_b32 s11, s65, 8
	s_mul_i32 s10, s65, 0x101
	s_and_b64 s[4:5], s[40:41], exec
	s_cselect_b32 s4, s10, s11
	s_add_i32 s4, s4, s64
	s_ashr_i32 s5, s4, 31
	s_lshr_b32 s5, s5, 23
	s_add_i32 s5, s4, s5
	s_ashr_i32 s10, s5, 9
	s_and_b32 s5, s5, 0xfe00
	s_sub_i32 s4, s4, s5
	s_sext_i32_i16 s5, s4
	s_bfe_u32 s5, s5, 0x3001c
	s_add_i32 s5, s4, s5
	s_sext_i32_i16 s11, s5
	s_and_b32 s5, s5, 0xfff8
	s_sub_i32 s4, s4, s5
	s_lshl_b32 s10, s10, 3
	s_sext_i32_i16 s4, s4
	s_add_i32 s4, s10, s4
	s_ashr_i32 s18, s11, 3

; #define LAS __attribute__((address_space(3)))
; __device__ __forceinline__ unsigned xb_ld(unsigned* p)              { return __hip_atomic_load(p, __ATOMIC_RELAXED, __HIP_MEMORY_SCOPE_AGENT); }
; __device__ __forceinline__ unsigned xb_add(unsigned* p, unsigned v) { return __hip_atomic_fetch_add(p, v, __ATOMIC_RELAXED, __HIP_MEMORY_SCOPE_AGENT); }
; __device__ __forceinline__ unsigned xb_xcc_id() { return (unsigned)__builtin_amdgcn_s_getreg((3 << 11) | 20) & 0xFu; }
; #define XB_SPIN(cond, bar) do { unsigned _sp = 0; while (cond) { __builtin_amdgcn_s_sleep(1); \
;     if ((++_sp & 255u) == 0u) { if (xb_ld(&(bar)[XB_TMO])) break; if (_sp > XB_SPIN_CAP) { atomicAdd(&(bar)[XB_TMO], 1u); break; } } } } while (0)
; __device__ __forceinline__ void xcd_barrier(unsigned* bar, volatile LAS unsigned* st, bool is_t0) {
;     asm volatile("s_waitcnt vmcnt(0)" ::: "memory");
;     __syncthreads();
;     if (is_t0) {
;         __builtin_amdgcn_s_waitcnt(0);
;         const unsigned x = xb_xcc_id();
;         unsigned nloc = st[0], nx = st[1];
;         if (nloc == 0u) { xcd_barrier_complete(bar, x, nloc, nx); st[0] = nloc; st[1] = nx; }
;         const unsigned old = xb_add(&bar[XB_XSUB(x)], 1u);
;         const unsigned gen = old / nloc;
;         if (old + 1u == (gen + 1u) * nloc) {
;             __builtin_amdgcn_fence(__ATOMIC_RELEASE, "agent");
;             asm volatile("s_waitcnt vmcnt(0)" ::: "memory");
;             const unsigned og = xb_add(&bar[XB_TOP], 1u);
;             const unsigned tg = og / nx;
;             if (og + 1u == (tg + 1u) * nx) xb_add(&bar[XB_TOPGEN], 1u);
;             else XB_SPIN(xb_ld(&bar[XB_TOPGEN]) == tg, bar);
;             __builtin_amdgcn_fence(__ATOMIC_ACQUIRE, "agent");
;             xb_add(&bar[XB_XGEN(x)], 1u);
;             asm volatile("s_waitcnt vmcnt(0)" ::: "memory");
;         } else {
;             XB_SPIN(xb_ld(&bar[XB_XGEN(x)]) == gen, bar);
;             __builtin_amdgcn_fence(__ATOMIC_ACQUIRE, "agent");
;             asm volatile("s_waitcnt vmcnt(0)" ::: "memory");
;         }
;     }
;     __syncthreads();
.LBB0_164:
	v_mbcnt_lo_u32_b32 v0, -1, 0
	v_mbcnt_hi_u32_b32 v0, -1, v0
	s_waitcnt vmcnt(0)
	s_waitcnt vmcnt(0)
	v_cmp_eq_u32_e32 vcc, 0, v0
	s_and_b64 s[0:1], vcc, s[36:37]
	s_barrier
	s_and_saveexec_b64 s[4:5], s[0:1]
	s_xor_b64 s[0:1], exec, s[4:5]
	s_cbranch_execz .LBB0_217
	s_waitcnt vmcnt(0) expcnt(0) lgkmcnt(0)
	v_mov_b32_e32 v250, 0x24080
	ds_read_b64 v[250:251], v250
	s_getreg_b32 s90, hwreg(HW_REG_XCC_ID, 0, 4)
	s_and_b32 s90, s90, 15
	s_lshl_b32 s91, s90, 8
	s_add_u32 s92, s34, s91
	s_addc_u32 s93, s35, 0
	s_add_u32 s92, s92, 0x1000
	s_addc_u32 s93, s93, 0
	s_add_u32 s94, s34, 0x3600
	s_addc_u32 s95, s35, 0
	s_lshl_b32 s91, s90, 7
	s_add_u32 s96, s94, s91
	s_addc_u32 s97, s95, 0
	v_mov_b32_e32 v253, 0
	v_mov_b32_e32 v252, 1
	s_waitcnt lgkmcnt(0)
	v_readfirstlane_b32 s98, v250
	v_readfirstlane_b32 s99, v251
	global_atomic_add v250, v253, v252, s[92:93] offset:1024 sc0
	s_mul_i32 s98, s98, 2
	s_mul_i32 s99, s99, 2
	s_waitcnt vmcnt(0)
	v_readfirstlane_b32 s91, v250
	s_add_i32 s91, s91, 1
	s_cmp_lg_u32 s91, s98
	s_cbranch_scc1 .Lfb1_poll
	buffer_wbl2 sc1
	s_waitcnt vmcnt(0)
	global_atomic_add v253, v252, s[94:95]
	global_atomic_add v253, v252, s[94:95] offset:128
	global_atomic_add v253, v252, s[94:95] offset:256
	global_atomic_add v253, v252, s[94:95] offset:384
	global_atomic_add v253, v252, s[94:95] offset:512
	global_atomic_add v253, v252, s[94:95] offset:640
	global_atomic_add v253, v252, s[94:95] offset:768
	global_atomic_add v253, v252, s[94:95] offset:896
	global_atomic_add v253, v252, s[94:95] offset:1024
	global_atomic_add v253, v252, s[94:95] offset:1152
	global_atomic_add v253, v252, s[94:95] offset:1280
	global_atomic_add v253, v252, s[94:95] offset:1408
	global_atomic_add v253, v252, s[94:95] offset:1536
	global_atomic_add v253, v252, s[94:95] offset:1664
	global_atomic_add v253, v252, s[94:95] offset:1792
	global_atomic_add v253, v252, s[94:95] offset:1920

; #define LAS __attribute__((address_space(3)))
; __device__ __forceinline__ unsigned xb_ld(unsigned* p)              { return __hip_atomic_load(p, __ATOMIC_RELAXED, __HIP_MEMORY_SCOPE_AGENT); }
; __device__ __forceinline__ unsigned xb_add(unsigned* p, unsigned v) { return __hip_atomic_fetch_add(p, v, __ATOMIC_RELAXED, __HIP_MEMORY_SCOPE_AGENT); }
; __device__ __forceinline__ unsigned xb_xcc_id() { return (unsigned)__builtin_amdgcn_s_getreg((3 << 11) | 20) & 0xFu; }
; #define XB_SPIN(cond, bar) do { unsigned _sp = 0; while (cond) { __builtin_amdgcn_s_sleep(1); \
;     if ((++_sp & 255u) == 0u) { if (xb_ld(&(bar)[XB_TMO])) break; if (_sp > XB_SPIN_CAP) { atomicAdd(&(bar)[XB_TMO], 1u); break; } } } } while (0)
; __device__ __forceinline__ void xcd_barrier(unsigned* bar, volatile LAS unsigned* st, bool is_t0) {
;     asm volatile("s_waitcnt vmcnt(0)" ::: "memory");
;     __syncthreads();
;     if (is_t0) {
;         __builtin_amdgcn_s_waitcnt(0);
;         const unsigned x = xb_xcc_id();
;         unsigned nloc = st[0], nx = st[1];
;         if (nloc == 0u) { xcd_barrier_complete(bar, x, nloc, nx); st[0] = nloc; st[1] = nx; }
;         const unsigned old = xb_add(&bar[XB_XSUB(x)], 1u);
;         const unsigned gen = old / nloc;
;         if (old + 1u == (gen + 1u) * nloc) {
;             __builtin_amdgcn_fence(__ATOMIC_RELEASE, "agent");
;             asm volatile("s_waitcnt vmcnt(0)" ::: "memory");
;             const unsigned og = xb_add(&bar[XB_TOP], 1u);
;             const unsigned tg = og / nx;
;             if (og + 1u == (tg + 1u) * nx) xb_add(&bar[XB_TOPGEN], 1u);
;             else XB_SPIN(xb_ld(&bar[XB_TOPGEN]) == tg, bar);
;             __builtin_amdgcn_fence(__ATOMIC_ACQUIRE, "agent");
;             xb_add(&bar[XB_XGEN(x)], 1u);
;             asm volatile("s_waitcnt vmcnt(0)" ::: "memory");
;         } else {
;             XB_SPIN(xb_ld(&bar[XB_XGEN(x)]) == gen, bar);
;             __builtin_amdgcn_fence(__ATOMIC_ACQUIRE, "agent");
;             asm volatile("s_waitcnt vmcnt(0)" ::: "memory");
;         }
;     }
;     __syncthreads();
.LBB0_239:
	s_or_b64 exec, exec, s[8:9]
	v_mbcnt_lo_u32_b32 v0, -1, 0
	v_mbcnt_hi_u32_b32 v0, -1, v0
	s_waitcnt vmcnt(0)
	s_nop 0
	v_cmp_eq_u32_e32 vcc, 0, v0
	s_and_b64 s[0:1], vcc, s[36:37]
	s_barrier
	s_and_saveexec_b64 s[8:9], s[0:1]
	s_xor_b64 s[0:1], exec, s[8:9]
	s_cbranch_execz .LBB0_292
	s_waitcnt vmcnt(0) expcnt(0) lgkmcnt(0)
	v_mov_b32_e32 v250, 0x24080
	ds_read_b64 v[250:251], v250
	s_getreg_b32 s90, hwreg(HW_REG_XCC_ID, 0, 4)
	s_and_b32 s90, s90, 15
	s_lshl_b32 s91, s90, 8
	s_add_u32 s92, s34, s91
	s_addc_u32 s93, s35, 0
	s_add_u32 s92, s92, 0x1000
	s_addc_u32 s93, s93, 0
	s_add_u32 s94, s34, 0x3600
	s_addc_u32 s95, s35, 0
	s_lshl_b32 s91, s90, 7
	s_add_u32 s96, s94, s91
	s_addc_u32 s97, s95, 0
	v_mov_b32_e32 v253, 0
	v_mov_b32_e32 v252, 1
	s_waitcnt lgkmcnt(0)
	v_readfirstlane_b32 s98, v250
	v_readfirstlane_b32 s99, v251
	global_atomic_add v250, v253, v252, s[92:93] offset:1024 sc0
	s_mul_i32 s98, s98, 3
	s_mul_i32 s99, s99, 3
	s_waitcnt vmcnt(0)
	v_readfirstlane_b32 s91, v250
	s_add_i32 s91, s91, 1
	s_cmp_lg_u32 s91, s98
	s_cbranch_scc1 .Lfb2_poll
	buffer_wbl2 sc1
	s_waitcnt vmcnt(0)
	global_atomic_add v253, v252, s[94:95]
	global_atomic_add v253, v252, s[94:95] offset:128
	global_atomic_add v253, v252, s[94:95] offset:256
	global_atomic_add v253, v252, s[94:95] offset:384
	global_atomic_add v253, v252, s[94:95] offset:512
	global_atomic_add v253, v252, s[94:95] offset:640
	global_atomic_add v253, v252, s[94:95] offset:768
	global_atomic_add v253, v252, s[94:95] offset:896
	global_atomic_add v253, v252, s[94:95] offset:1024
	global_atomic_add v253, v252, s[94:95] offset:1152
	global_atomic_add v253, v252, s[94:95] offset:1280
	global_atomic_add v253, v252, s[94:95] offset:1408
	global_atomic_add v253, v252, s[94:95] offset:1536
	global_atomic_add v253, v252, s[94:95] offset:1664
	global_atomic_add v253, v252, s[94:95] offset:1792
	global_atomic_add v253, v252, s[94:95] offset:1920

; #define LAS __attribute__((address_space(3)))
; __device__ __forceinline__ unsigned xb_ld(unsigned* p)              { return __hip_atomic_load(p, __ATOMIC_RELAXED, __HIP_MEMORY_SCOPE_AGENT); }
; __device__ __forceinline__ unsigned xb_add(unsigned* p, unsigned v) { return __hip_atomic_fetch_add(p, v, __ATOMIC_RELAXED, __HIP_MEMORY_SCOPE_AGENT); }
; __device__ __forceinline__ unsigned xb_xcc_id() { return (unsigned)__builtin_amdgcn_s_getreg((3 << 11) | 20) & 0xFu; }
; #define XB_SPIN(cond, bar) do { unsigned _sp = 0; while (cond) { __builtin_amdgcn_s_sleep(1); \
;     if ((++_sp & 255u) == 0u) { if (xb_ld(&(bar)[XB_TMO])) break; if (_sp > XB_SPIN_CAP) { atomicAdd(&(bar)[XB_TMO], 1u); break; } } } } while (0)
; __device__ __forceinline__ void xcd_barrier(unsigned* bar, volatile LAS unsigned* st, bool is_t0) {
;     asm volatile("s_waitcnt vmcnt(0)" ::: "memory");
;     __syncthreads();
;     if (is_t0) {
;         __builtin_amdgcn_s_waitcnt(0);
;         const unsigned x = xb_xcc_id();
;         unsigned nloc = st[0], nx = st[1];
;         if (nloc == 0u) { xcd_barrier_complete(bar, x, nloc, nx); st[0] = nloc; st[1] = nx; }
;         const unsigned old = xb_add(&bar[XB_XSUB(x)], 1u);
;         const unsigned gen = old / nloc;
;         if (old + 1u == (gen + 1u) * nloc) {
;             __builtin_amdgcn_fence(__ATOMIC_RELEASE, "agent");
;             asm volatile("s_waitcnt vmcnt(0)" ::: "memory");
;             const unsigned og = xb_add(&bar[XB_TOP], 1u);
;             const unsigned tg = og / nx;
;             if (og + 1u == (tg + 1u) * nx) xb_add(&bar[XB_TOPGEN], 1u);
;             else XB_SPIN(xb_ld(&bar[XB_TOPGEN]) == tg, bar);
;             __builtin_amdgcn_fence(__ATOMIC_ACQUIRE, "agent");
;             xb_add(&bar[XB_XGEN(x)], 1u);
;             asm volatile("s_waitcnt vmcnt(0)" ::: "memory");
;         } else {
;             XB_SPIN(xb_ld(&bar[XB_XGEN(x)]) == gen, bar);
;             __builtin_amdgcn_fence(__ATOMIC_ACQUIRE, "agent");
;             asm volatile("s_waitcnt vmcnt(0)" ::: "memory");
;         }
;     }
;     __syncthreads();
.LBB0_297:
	s_or_b64 exec, exec, s[8:9]
	v_mbcnt_lo_u32_b32 v0, -1, 0
	v_mbcnt_hi_u32_b32 v0, -1, v0
	s_waitcnt vmcnt(0)
	s_nop 0
	v_cmp_eq_u32_e32 vcc, 0, v0
	s_and_b64 s[0:1], vcc, s[36:37]
	s_barrier
	s_and_saveexec_b64 s[6:7], s[0:1]
	s_xor_b64 s[0:1], exec, s[6:7]
	s_cbranch_execz .LBB0_350
	s_waitcnt vmcnt(0) expcnt(0) lgkmcnt(0)
	v_mov_b32_e32 v250, 0x24080
	ds_read_b64 v[250:251], v250
	s_getreg_b32 s90, hwreg(HW_REG_XCC_ID, 0, 4)
	s_and_b32 s90, s90, 15
	s_lshl_b32 s91, s90, 8
	s_add_u32 s92, s34, s91
	s_addc_u32 s93, s35, 0
	s_add_u32 s92, s92, 0x1000
	s_addc_u32 s93, s93, 0
	s_add_u32 s94, s34, 0x3600
	s_addc_u32 s95, s35, 0
	s_lshl_b32 s91, s90, 7
	s_add_u32 s96, s94, s91
	s_addc_u32 s97, s95, 0
	v_mov_b32_e32 v253, 0
	v_mov_b32_e32 v252, 1
	s_waitcnt lgkmcnt(0)
	v_readfirstlane_b32 s98, v250
	v_readfirstlane_b32 s99, v251
	global_atomic_add v250, v253, v252, s[92:93] offset:1024 sc0
	s_mul_i32 s98, s98, 4
	s_mul_i32 s99, s99, 4
	s_waitcnt vmcnt(0)
	v_readfirstlane_b32 s91, v250
	s_add_i32 s91, s91, 1
	s_cmp_lg_u32 s91, s98
	s_cbranch_scc1 .Lfb3_poll
	buffer_wbl2 sc1
	s_waitcnt vmcnt(0)
	global_atomic_add v253, v252, s[94:95]
	global_atomic_add v253, v252, s[94:95] offset:128
	global_atomic_add v253, v252, s[94:95] offset:256
	global_atomic_add v253, v252, s[94:95] offset:384
	global_atomic_add v253, v252, s[94:95] offset:512
	global_atomic_add v253, v252, s[94:95] offset:640
	global_atomic_add v253, v252, s[94:95] offset:768
	global_atomic_add v253, v252, s[94:95] offset:896
	global_atomic_add v253, v252, s[94:95] offset:1024
	global_atomic_add v253, v252, s[94:95] offset:1152
	global_atomic_add v253, v252, s[94:95] offset:1280
	global_atomic_add v253, v252, s[94:95] offset:1408
	global_atomic_add v253, v252, s[94:95] offset:1536
	global_atomic_add v253, v252, s[94:95] offset:1664
	global_atomic_add v253, v252, s[94:95] offset:1792
	global_atomic_add v253, v252, s[94:95] offset:1920

; #define LAS __attribute__((address_space(3)))
; __device__ __forceinline__ unsigned xb_ld(unsigned* p)              { return __hip_atomic_load(p, __ATOMIC_RELAXED, __HIP_MEMORY_SCOPE_AGENT); }
; __device__ __forceinline__ unsigned xb_add(unsigned* p, unsigned v) { return __hip_atomic_fetch_add(p, v, __ATOMIC_RELAXED, __HIP_MEMORY_SCOPE_AGENT); }
; __device__ __forceinline__ unsigned xb_xcc_id() { return (unsigned)__builtin_amdgcn_s_getreg((3 << 11) | 20) & 0xFu; }
; #define XB_SPIN(cond, bar) do { unsigned _sp = 0; while (cond) { __builtin_amdgcn_s_sleep(1); \
;     if ((++_sp & 255u) == 0u) { if (xb_ld(&(bar)[XB_TMO])) break; if (_sp > XB_SPIN_CAP) { atomicAdd(&(bar)[XB_TMO], 1u); break; } } } } while (0)
; __device__ __forceinline__ void xcd_barrier(unsigned* bar, volatile LAS unsigned* st, bool is_t0) {
;     asm volatile("s_waitcnt vmcnt(0)" ::: "memory");
;     __syncthreads();
;     if (is_t0) {
;         __builtin_amdgcn_s_waitcnt(0);
;         const unsigned x = xb_xcc_id();
;         unsigned nloc = st[0], nx = st[1];
;         if (nloc == 0u) { xcd_barrier_complete(bar, x, nloc, nx); st[0] = nloc; st[1] = nx; }
;         const unsigned old = xb_add(&bar[XB_XSUB(x)], 1u);
;         const unsigned gen = old / nloc;
;         if (old + 1u == (gen + 1u) * nloc) {
;             __builtin_amdgcn_fence(__ATOMIC_RELEASE, "agent");
;             asm volatile("s_waitcnt vmcnt(0)" ::: "memory");
;             const unsigned og = xb_add(&bar[XB_TOP], 1u);
;             const unsigned tg = og / nx;
;             if (og + 1u == (tg + 1u) * nx) xb_add(&bar[XB_TOPGEN], 1u);
;             else XB_SPIN(xb_ld(&bar[XB_TOPGEN]) == tg, bar);
;             __builtin_amdgcn_fence(__ATOMIC_ACQUIRE, "agent");
;             xb_add(&bar[XB_XGEN(x)], 1u);
;             asm volatile("s_waitcnt vmcnt(0)" ::: "memory");
;         } else {
;             XB_SPIN(xb_ld(&bar[XB_XGEN(x)]) == gen, bar);
;             __builtin_amdgcn_fence(__ATOMIC_ACQUIRE, "agent");
;             asm volatile("s_waitcnt vmcnt(0)" ::: "memory");
;         }
;     }
;     __syncthreads();
.LBB0_405:
	s_barrier
	v_mbcnt_lo_u32_b32 v0, -1, 0
	v_mbcnt_hi_u32_b32 v0, -1, v0
	s_waitcnt vmcnt(0)
	s_nop 0
	v_cmp_eq_u32_e32 vcc, 0, v0
	s_and_b64 s[0:1], vcc, s[36:37]
	s_barrier
	s_and_saveexec_b64 s[4:5], s[0:1]
	s_xor_b64 s[0:1], exec, s[4:5]
	s_cbranch_execz .LBB0_458
	s_waitcnt vmcnt(0) expcnt(0) lgkmcnt(0)
	v_mov_b32_e32 v250, 0x24080
	ds_read_b64 v[250:251], v250
	s_getreg_b32 s90, hwreg(HW_REG_XCC_ID, 0, 4)
	s_and_b32 s90, s90, 15
	s_lshl_b32 s91, s90, 8
	s_add_u32 s92, s34, s91
	s_addc_u32 s93, s35, 0
	s_add_u32 s92, s92, 0x1000
	s_addc_u32 s93, s93, 0
	s_add_u32 s94, s34, 0x3600
	s_addc_u32 s95, s35, 0
	s_lshl_b32 s91, s90, 7
	s_add_u32 s96, s94, s91
	s_addc_u32 s97, s95, 0
	v_mov_b32_e32 v253, 0
	v_mov_b32_e32 v252, 1
	s_waitcnt lgkmcnt(0)
	v_readfirstlane_b32 s98, v250
	v_readfirstlane_b32 s99, v251
	global_atomic_add v250, v253, v252, s[92:93] offset:1024 sc0
	s_mul_i32 s98, s98, 5
	s_mul_i32 s99, s99, 5
	s_waitcnt vmcnt(0)
	v_readfirstlane_b32 s91, v250
	s_add_i32 s91, s91, 1
	s_cmp_lg_u32 s91, s98
	s_cbranch_scc1 .Lfb4_poll
	buffer_wbl2 sc1
	s_waitcnt vmcnt(0)
	global_atomic_add v253, v252, s[94:95]
	global_atomic_add v253, v252, s[94:95] offset:128
	global_atomic_add v253, v252, s[94:95] offset:256
	global_atomic_add v253, v252, s[94:95] offset:384
	global_atomic_add v253, v252, s[94:95] offset:512
	global_atomic_add v253, v252, s[94:95] offset:640
	global_atomic_add v253, v252, s[94:95] offset:768
	global_atomic_add v253, v252, s[94:95] offset:896
	global_atomic_add v253, v252, s[94:95] offset:1024
	global_atomic_add v253, v252, s[94:95] offset:1152
	global_atomic_add v253, v252, s[94:95] offset:1280
	global_atomic_add v253, v252, s[94:95] offset:1408
	global_atomic_add v253, v252, s[94:95] offset:1536
	global_atomic_add v253, v252, s[94:95] offset:1664
	global_atomic_add v253, v252, s[94:95] offset:1792
	global_atomic_add v253, v252, s[94:95] offset:1920

; #define LAS __attribute__((address_space(3)))
; __device__ __forceinline__ unsigned xb_ld(unsigned* p)              { return __hip_atomic_load(p, __ATOMIC_RELAXED, __HIP_MEMORY_SCOPE_AGENT); }
; __device__ __forceinline__ unsigned xb_add(unsigned* p, unsigned v) { return __hip_atomic_fetch_add(p, v, __ATOMIC_RELAXED, __HIP_MEMORY_SCOPE_AGENT); }
; __device__ __forceinline__ unsigned xb_xcc_id() { return (unsigned)__builtin_amdgcn_s_getreg((3 << 11) | 20) & 0xFu; }
; #define XB_SPIN(cond, bar) do { unsigned _sp = 0; while (cond) { __builtin_amdgcn_s_sleep(1); \
;     if ((++_sp & 255u) == 0u) { if (xb_ld(&(bar)[XB_TMO])) break; if (_sp > XB_SPIN_CAP) { atomicAdd(&(bar)[XB_TMO], 1u); break; } } } } while (0)
; __device__ __forceinline__ void xcd_barrier(unsigned* bar, volatile LAS unsigned* st, bool is_t0) {
;     asm volatile("s_waitcnt vmcnt(0)" ::: "memory");
;     __syncthreads();
;     if (is_t0) {
;         __builtin_amdgcn_s_waitcnt(0);
;         const unsigned x = xb_xcc_id();
;         unsigned nloc = st[0], nx = st[1];
;         if (nloc == 0u) { xcd_barrier_complete(bar, x, nloc, nx); st[0] = nloc; st[1] = nx; }
;         const unsigned old = xb_add(&bar[XB_XSUB(x)], 1u);
;         const unsigned gen = old / nloc;
;         if (old + 1u == (gen + 1u) * nloc) {
;             __builtin_amdgcn_fence(__ATOMIC_RELEASE, "agent");
;             asm volatile("s_waitcnt vmcnt(0)" ::: "memory");
;             const unsigned og = xb_add(&bar[XB_TOP], 1u);
;             const unsigned tg = og / nx;
;             if (og + 1u == (tg + 1u) * nx) xb_add(&bar[XB_TOPGEN], 1u);
;             else XB_SPIN(xb_ld(&bar[XB_TOPGEN]) == tg, bar);
;             __builtin_amdgcn_fence(__ATOMIC_ACQUIRE, "agent");
;             xb_add(&bar[XB_XGEN(x)], 1u);
;             asm volatile("s_waitcnt vmcnt(0)" ::: "memory");
;         } else {
;             XB_SPIN(xb_ld(&bar[XB_XGEN(x)]) == gen, bar);
;             __builtin_amdgcn_fence(__ATOMIC_ACQUIRE, "agent");
;             asm volatile("s_waitcnt vmcnt(0)" ::: "memory");
;         }
;     }
;     __syncthreads();
.LBB0_488:
	v_mbcnt_lo_u32_b32 v0, -1, 0
	v_mbcnt_hi_u32_b32 v0, -1, v0
	s_waitcnt vmcnt(0)
	s_nop 0
	v_cmp_eq_u32_e32 vcc, 0, v0
	s_and_b64 s[0:1], vcc, s[36:37]
	s_barrier
	s_and_saveexec_b64 s[4:5], s[0:1]
	s_xor_b64 s[0:1], exec, s[4:5]
	s_cbranch_execz .LBB0_541
	s_waitcnt vmcnt(0) expcnt(0) lgkmcnt(0)
	v_mov_b32_e32 v250, 0x24080
	ds_read_b64 v[250:251], v250
	s_getreg_b32 s90, hwreg(HW_REG_XCC_ID, 0, 4)
	s_and_b32 s90, s90, 15
	s_lshl_b32 s91, s90, 8
	s_add_u32 s92, s34, s91
	s_addc_u32 s93, s35, 0
	s_add_u32 s92, s92, 0x1000
	s_addc_u32 s93, s93, 0
	s_add_u32 s94, s34, 0x3600
	s_addc_u32 s95, s35, 0
	s_lshl_b32 s91, s90, 7
	s_add_u32 s96, s94, s91
	s_addc_u32 s97, s95, 0
	v_mov_b32_e32 v253, 0
	v_mov_b32_e32 v252, 1
	s_waitcnt lgkmcnt(0)
	v_readfirstlane_b32 s98, v250
	v_readfirstlane_b32 s99, v251
	global_atomic_add v250, v253, v252, s[92:93] offset:1024 sc0
	s_mul_i32 s98, s98, 6
	s_mul_i32 s99, s99, 6
	s_waitcnt vmcnt(0)
	v_readfirstlane_b32 s91, v250
	s_add_i32 s91, s91, 1
	s_cmp_lg_u32 s91, s98
	s_cbranch_scc1 .Lfb5_poll
	buffer_wbl2 sc1
	s_waitcnt vmcnt(0)
	global_atomic_add v253, v252, s[94:95]
	global_atomic_add v253, v252, s[94:95] offset:128
	global_atomic_add v253, v252, s[94:95] offset:256
	global_atomic_add v253, v252, s[94:95] offset:384
	global_atomic_add v253, v252, s[94:95] offset:512
	global_atomic_add v253, v252, s[94:95] offset:640
	global_atomic_add v253, v252, s[94:95] offset:768
	global_atomic_add v253, v252, s[94:95] offset:896
	global_atomic_add v253, v252, s[94:95] offset:1024
	global_atomic_add v253, v252, s[94:95] offset:1152
	global_atomic_add v253, v252, s[94:95] offset:1280
	global_atomic_add v253, v252, s[94:95] offset:1408
	global_atomic_add v253, v252, s[94:95] offset:1536
	global_atomic_add v253, v252, s[94:95] offset:1664
	global_atomic_add v253, v252, s[94:95] offset:1792
	global_atomic_add v253, v252, s[94:95] offset:1920
